# S5 final pass t-loop also on f32 MFMA 32x32x2 (B*u), recurrence as 4 v_fma per token in MFMA D registers
# speedup vs baseline: 1.0271x; 1.0135x over previous
; template <bool FINAL>
; __device__ __forceinline__ void s5_wave(const Params& P, int j, int g, int idx0, int stride, char* ldsw) {
;     ...
;   const float lr = P.in[I_S5LRE][jg * 64 + p], li = P.in[I_S5LIM][jg * 64 + p];
;   const float dt = expf(P.in[I_S5LOGDT][jg]);
;   const float er = expf(lr * dt);
;   float sn, cs;
;   sincosf(li * dt, &sn, &cs);
;   const float lbr = er * cs, lbi = er * sn;
;   const float nr = lbr - 1.f, ni = lbi;
;   const float den = 1.f / (lr * lr + li * li);
;   const float cr = (nr * lr + ni * li) * den, ci = (ni * lr - nr * li) * den;
;   typedef float f32x2 __attribute__((ext_vector_type(2)));
;   f32x2 bb[16];
;   {
;     const float4* br4 = reinterpret_cast<const float4*>(P.in[I_S5BRE] + ((size_t)jg * 64 + p) * 16);
;     const float4* bi4 = reinterpret_cast<const float4*>(P.in[I_S5BIM] + ((size_t)jg * 64 + p) * 16);
;     ...
;   const int fr = lane & 15, fq = lane >> 4;
;   bf16x8 bc[4];
;   f32x4 dv4 = {0.f, 0.f, 0.f, 0.f};
;   if (FINAL) {
;     const float* crp = P.in[I_S5CRE] + ((size_t)jg * 16 + fr) * 64;
;     const float* cip = P.in[I_S5CIM] + ((size_t)jg * 16 + fr) * 64;
; #pragma unroll
;     for (int ks = 0; ks < 4; ++ks) {
;       float4 a = *reinterpret_cast<const float4*>(crp + ks * 16 + fq * 4);
;       float4 c = *reinterpret_cast<const float4*>(cip + ks * 16 + fq * 4);
;       union { bf16x8 v; uint32_t w[4]; } uu_;
;       uu_.w[0] = pack2(a.x, -c.x); uu_.w[1] = pack2(a.y, -c.y); uu_.w[2] = pack2(a.z, -c.z); uu_.w[3] = pack2(a.w, -c.w);
;       bc[ks] = uu_.v;
;     }
;     dv4 = *reinterpret_cast<const f32x4*>(P.in[I_S5D] + j * 512 + g * 16 + 4 * fq);
.LBB0_428:
	s_or_b64 exec, exec, s[0:1]
	v_readlane_b32 s0, v255, 0
	v_readlane_b32 s1, v255, 1
	v_ashrrev_i32_e32 v4, 2, v48
	v_and_b32_e32 v90, 15, v48
	s_lshl_b64 s[0:1], s[0:1], 2
	v_readlane_b32 s4, v250, 50
	v_and_b32_e32 v50, -4, v4
	v_lshl_or_b32 v0, v90, 8, s0
	v_mov_b32_e32 v1, s1
	v_readlane_b32 s12, v250, 58
	v_readlane_b32 s13, v250, 59
	v_ashrrev_i32_e32 v51, 31, v50
	v_readlane_b32 s14, v250, 60
	v_readlane_b32 s15, v250, 61
	v_lshl_add_u64 v[2:3], s[12:13], 0, v[0:1]
	v_lshlrev_b64 v[4:5], 2, v[50:51]
	v_lshl_add_u64 v[0:1], s[14:15], 0, v[0:1]
	v_lshl_add_u64 v[22:23], v[2:3], 0, v[4:5]
	v_lshl_add_u64 v[24:25], v[0:1], 0, v[4:5]
	global_load_dwordx4 v[0:3], v[22:23], off
	global_load_dwordx4 v[4:7], v[24:25], off
	v_readlane_b32 s0, v251, 63
	v_readlane_b32 s1, v252, 0
	s_andn2_b64 vcc, exec, s[0:1]
	v_readlane_b32 s5, v250, 51
	v_readlane_b32 s6, v250, 52
	v_readlane_b32 s7, v250, 53
	v_readlane_b32 s8, v250, 54
	v_readlane_b32 s9, v250, 55
	v_readlane_b32 s10, v250, 56
	v_readlane_b32 s11, v250, 57
	v_readlane_b32 s16, v250, 62
	v_readlane_b32 s17, v250, 63
	v_readlane_b32 s18, v251, 0
	v_readlane_b32 s19, v251, 1
	s_waitcnt vmcnt(0)
	v_xor_b32_e32 v4, 0x80000000, v4
	v_cvt_pk_bf16_f32 v0, v0, v4
	v_xor_b32_e32 v4, 0x80000000, v5
	v_cvt_pk_bf16_f32 v1, v1, v4
	v_xor_b32_e32 v4, 0x80000000, v6
	v_cvt_pk_bf16_f32 v2, v2, v4
	v_xor_b32_e32 v4, 0x80000000, v7
	v_cvt_pk_bf16_f32 v3, v3, v4
	global_load_dwordx4 v[4:7], v[22:23], off offset:64
	global_load_dwordx4 v[8:11], v[24:25], off offset:64
	s_waitcnt vmcnt(0)
	v_xor_b32_e32 v8, 0x80000000, v8
	v_cvt_pk_bf16_f32 v4, v4, v8
	v_xor_b32_e32 v8, 0x80000000, v9
	v_cvt_pk_bf16_f32 v5, v5, v8
	v_xor_b32_e32 v8, 0x80000000, v10
	v_cvt_pk_bf16_f32 v6, v6, v8
	v_xor_b32_e32 v8, 0x80000000, v11
	v_cvt_pk_bf16_f32 v7, v7, v8
	global_load_dwordx4 v[8:11], v[22:23], off offset:128
	global_load_dwordx4 v[12:15], v[24:25], off offset:128
	s_waitcnt vmcnt(0)
	v_xor_b32_e32 v12, 0x80000000, v12
	v_cvt_pk_bf16_f32 v8, v8, v12
	v_xor_b32_e32 v12, 0x80000000, v13
	v_cvt_pk_bf16_f32 v9, v9, v12
	v_xor_b32_e32 v12, 0x80000000, v14
	v_cvt_pk_bf16_f32 v10, v10, v12
	v_xor_b32_e32 v12, 0x80000000, v15
	v_cvt_pk_bf16_f32 v11, v11, v12
	global_load_dwordx4 v[12:15], v[22:23], off offset:192
	s_nop 0
	global_load_dwordx4 v[22:25], v[24:25], off offset:192
	s_waitcnt vmcnt(0)
	v_xor_b32_e32 v21, 0x80000000, v22
	v_cvt_pk_bf16_f32 v12, v12, v21
	v_xor_b32_e32 v21, 0x80000000, v23
	v_cvt_pk_bf16_f32 v13, v13, v21
	v_xor_b32_e32 v21, 0x80000000, v24
	v_cvt_pk_bf16_f32 v14, v14, v21
	v_xor_b32_e32 v21, 0x80000000, v25
	v_cvt_pk_bf16_f32 v15, v15, v21
	s_cbranch_vccnz .LBB0_440
	v_mul_f32_e32 v18, v56, v18
	v_mul_f32_e32 v21, 0x3fb8aa3b, v18
	s_mov_b32 s0, 0x3fb8aa3b
	v_fma_f32 v22, v18, s0, -v21
	v_rndne_f32_e32 v23, v21
	v_fmac_f32_e32 v22, 0x32a5705f, v18
	v_sub_f32_e32 v21, v21, v23
	v_add_f32_e32 v21, v21, v22
	v_exp_f32_e32 v21, v21
	v_cvt_i32_f32_e32 v22, v23
	s_mov_b32 s0, 0xc2ce8ed0
	v_cmp_ngt_f32_e32 vcc, s0, v18
	s_mov_b32 s0, 0x42b17218
	v_ldexp_f32 v21, v21, v22
	v_cndmask_b32_e32 v21, 0, v21, vcc
	v_cmp_nlt_f32_e32 vcc, s0, v18
	v_xor_b32_e32 v17, v17, v16
	s_brev_b32 s0, 1
	v_cndmask_b32_e32 v18, v226, v21, vcc
	v_mul_f32_e32 v21, v19, v19
	v_fmamk_f32 v22, v21, 0xb94c1982, v219
	v_fmaak_f32 v22, v21, v22, 0xbe2aaa9d
	v_mul_f32_e32 v22, v21, v22
	v_fmac_f32_e32 v19, v19, v22
	v_fmamk_f32 v22, v21, 0x37d75334, v220
	v_fmaak_f32 v22, v21, v22, 0x3d2aabf7
	v_fmaak_f32 v22, v21, v22, 0xbf000004
	v_fma_f32 v21, v21, v22, 1.0
	v_lshlrev_b32_e32 v22, 30, v20
	v_and_b32_e32 v20, 1, v20
	v_cmp_eq_u32_e32 vcc, 0, v20
	v_and_b32_e32 v23, 0x80000000, v22
	v_ashrrev_i32_e32 v49, 31, v48
	v_cndmask_b32_e32 v20, v21, v19, vcc
	v_xor_b32_e32 v19, 0x80000000, v19
	v_cndmask_b32_e32 v19, v19, v21, vcc
	v_xor_b32_e32 v17, v17, v20
	v_bitop3_b32 v19, v19, v22, s0 bitop3:0x78
	s_movk_i32 s0, 0x1f8
	v_xor_b32_e32 v17, v17, v23
	v_cmp_class_f32_e64 vcc, v16, s0
	v_readlane_b32 s4, v250, 50
	v_readlane_b32 s8, v250, 54
	v_cndmask_b32_e32 v16, v229, v19, vcc
	v_cndmask_b32_e32 v17, v229, v17, vcc
	v_mul_f32_e32 v52, v18, v16
	v_mul_f32_e32 v55, v18, v17
	v_fma_f32 v54, v18, v16, -1.0
	v_pk_mul_f32 v[16:17], v[56:57], v[56:57]
	v_readlane_b32 s9, v250, 55
	v_add_f32_e32 v16, v16, v17
	v_div_scale_f32 v17, s[0:1], v16, v16, 1.0
	v_rcp_f32_e32 v18, v17
	v_readlane_b32 s0, v255, 0
	v_readlane_b32 s1, v255, 1
	v_readlane_b32 s10, v250, 56
	v_fma_f32 v19, -v17, v18, 1.0
	v_fmac_f32_e32 v18, v19, v18
	v_div_scale_f32 v19, vcc, 1.0, v16, 1.0
	v_mul_f32_e32 v20, v19, v18
	v_fma_f32 v21, -v17, v20, v19
	v_fmac_f32_e32 v20, v21, v18
	v_fma_f32 v17, -v17, v20, v19
	v_div_fmas_f32 v17, v17, v18, v20
	v_div_fixup_f32 v58, v17, v16, 1.0
	v_lshl_add_u64 v[16:17], v[48:49], 4, s[0:1]
	v_lshlrev_b64 v[16:17], 2, v[16:17]
	v_readlane_b32 s11, v250, 57
	v_lshl_add_u64 v[20:21], s[8:9], 0, v[16:17]
	v_mov_b32_e32 v60, v57
	v_lshl_add_u64 v[44:45], s[10:11], 0, v[16:17]
	global_load_dwordx4 v[16:19], v[20:21], off offset:48
	global_load_dwordx4 v[24:27], v[20:21], off offset:32
	global_load_dwordx4 v[32:35], v[20:21], off offset:16
	global_load_dwordx4 v[40:43], v[20:21], off
	s_nop 0
	global_load_dwordx4 v[20:23], v[44:45], off offset:48
	global_load_dwordx4 v[28:31], v[44:45], off offset:32
	global_load_dwordx4 v[36:39], v[44:45], off offset:16
	s_nop 0
	global_load_dwordx4 v[44:47], v[44:45], off
	v_pk_mul_f32 v[60:61], v[60:61], v[54:55] op_sel:[0,1] op_sel_hi:[0,0]
	v_pk_fma_f32 v[62:63], v[56:57], v[54:55], v[60:61]
	v_pk_fma_f32 v[56:57], v[56:57], v[54:55], v[60:61] op_sel_hi:[0,1,1] neg_lo:[0,0,1] neg_hi:[0,0,1]
	v_mov_b32_e32 v63, v57
	v_pk_mul_f32 v[68:69], v[58:59], v[62:63] op_sel_hi:[0,1]
	v_readlane_b32 s0, v255, 2
	v_readlane_b32 s1, v255, 3
	v_mov_b32_e32 v53, v52
	v_readlane_b32 s5, v250, 51
	v_readlane_b32 s6, v250, 52
	v_readlane_b32 s7, v250, 53
	v_readlane_b32 s12, v250, 58
	v_readlane_b32 s13, v250, 59
	v_readlane_b32 s14, v250, 60
	v_readlane_b32 s15, v250, 61
	v_readlane_b32 s16, v250, 62
	v_readlane_b32 s17, v250, 63
	v_readlane_b32 s18, v251, 0
	v_readlane_b32 s19, v251, 1
	s_waitcnt vmcnt(4)
; template <bool FINAL>
; __device__ __forceinline__ void s5_wave(const Params& P, int j, int g, int idx0, int stride, char* ldsw) {
;     ...
; #pragma unroll
;     for (int q = 0; q < 4; ++q) {
;       float4 a = br4[q], c = bi4[q];
;       bb[4 * q + 0] = (f32x2){cr * a.x - ci * c.x, cr * c.x + ci * a.x};
;       bb[4 * q + 1] = (f32x2){cr * a.y - ci * c.y, cr * c.y + ci * a.y};
;       bb[4 * q + 2] = (f32x2){cr * a.z - ci * c.z, cr * c.z + ci * a.z};
;       bb[4 * q + 3] = (f32x2){cr * a.w - ci * c.w, cr * c.w + ci * a.w};
;     }
;   }
	v_mov_b32_e32 v54, v43
	s_waitcnt vmcnt(0)
	v_pk_mul_f32 v[58:59], v[44:45], v[68:69] op_sel:[0,1] op_sel_hi:[0,0]
	v_pk_fma_f32 v[56:57], v[40:41], v[68:69], v[58:59] neg_lo:[0,0,1] neg_hi:[0,0,1]
	v_pk_fma_f32 v[58:59], v[40:41], v[68:69], v[58:59] op_sel_hi:[0,1,1]
	v_mov_b32_e32 v57, v59
	v_pk_mul_f32 v[58:59], v[44:45], v[68:69] op_sel:[1,1] op_sel_hi:[1,0]
	v_mov_b32_e32 v44, v41
	v_pk_fma_f32 v[44:45], v[44:45], v[68:69], v[58:59] neg_lo:[0,0,1] neg_hi:[0,0,1]
	v_pk_fma_f32 v[40:41], v[40:41], v[68:69], v[58:59] op_sel:[1,0,0]
	v_pk_mul_f32 v[58:59], v[46:47], v[68:69] op_sel:[0,1] op_sel_hi:[0,0]
	v_mov_b32_e32 v45, v41
	v_pk_fma_f32 v[40:41], v[42:43], v[68:69], v[58:59] neg_lo:[0,0,1] neg_hi:[0,0,1]
	v_pk_fma_f32 v[58:59], v[42:43], v[68:69], v[58:59] op_sel_hi:[0,1,1]
	v_mov_b32_e32 v42, v47
	v_pk_mul_f32 v[46:47], v[42:43], v[68:69] op_sel:[0,1] op_sel_hi:[0,0]
	v_mov_b32_e32 v42, v43
	v_mov_b32_e32 v41, v59
	v_pk_fma_f32 v[42:43], v[42:43], v[68:69], v[46:47] neg_lo:[0,0,1] neg_hi:[0,0,1]
	v_pk_fma_f32 v[46:47], v[54:55], v[68:69], v[46:47] op_sel_hi:[0,1,1]
	v_pk_mul_f32 v[58:59], v[36:37], v[68:69] op_sel:[0,1] op_sel_hi:[0,0]
	v_mov_b32_e32 v43, v47
	v_pk_fma_f32 v[46:47], v[32:33], v[68:69], v[58:59] neg_lo:[0,0,1] neg_hi:[0,0,1]
	v_pk_fma_f32 v[58:59], v[32:33], v[68:69], v[58:59] op_sel_hi:[0,1,1]
	v_mov_b32_e32 v47, v59
	v_pk_mul_f32 v[58:59], v[68:69], v[36:37] op_sel:[1,1] op_sel_hi:[0,1]
	v_mov_b32_e32 v36, v33
	v_pk_fma_f32 v[36:37], v[36:37], v[68:69], v[58:59] neg_lo:[0,0,1] neg_hi:[0,0,1]
	v_pk_fma_f32 v[32:33], v[32:33], v[68:69], v[58:59] op_sel:[1,0,0]
	v_pk_mul_f32 v[58:59], v[68:69], v[38:39] op_sel:[1,0] op_sel_hi:[0,0]
	v_mov_b32_e32 v37, v33
	v_pk_fma_f32 v[32:33], v[34:35], v[68:69], v[58:59] neg_lo:[0,0,1] neg_hi:[0,0,1]
	v_pk_fma_f32 v[58:59], v[34:35], v[68:69], v[58:59] op_sel_hi:[0,1,1]
	v_mov_b32_e32 v34, v39
	v_pk_mul_f32 v[38:39], v[68:69], v[34:35] op_sel:[1,0] op_sel_hi:[0,0]
	v_mov_b32_e32 v34, v35
	v_mov_b32_e32 v54, v35
	v_mov_b32_e32 v33, v59
	v_pk_fma_f32 v[34:35], v[34:35], v[68:69], v[38:39] neg_lo:[0,0,1] neg_hi:[0,0,1]
	v_pk_fma_f32 v[38:39], v[54:55], v[68:69], v[38:39] op_sel_hi:[0,1,1]
	v_pk_mul_f32 v[58:59], v[68:69], v[28:29] op_sel:[1,0] op_sel_hi:[0,0]
	v_mov_b32_e32 v35, v39
	v_pk_fma_f32 v[38:39], v[68:69], v[24:25], v[58:59] neg_lo:[0,0,1] neg_hi:[0,0,1]
	v_pk_fma_f32 v[58:59], v[68:69], v[24:25], v[58:59] op_sel_hi:[1,0,1]
	v_mov_b32_e32 v54, v27
	v_mov_b32_e32 v39, v59
	v_pk_mul_f32 v[58:59], v[68:69], v[28:29] op_sel:[1,1] op_sel_hi:[0,1]
	v_mov_b32_e32 v28, v25
	v_pk_fma_f32 v[28:29], v[68:69], v[28:29], v[58:59] neg_lo:[0,0,1] neg_hi:[0,0,1]
	v_pk_fma_f32 v[24:25], v[68:69], v[24:25], v[58:59] op_sel:[0,1,0]
	s_nop 0
	v_mov_b32_e32 v29, v25
	v_pk_mul_f32 v[24:25], v[68:69], v[30:31] op_sel:[1,0] op_sel_hi:[0,0]
	v_pk_fma_f32 v[58:59], v[68:69], v[26:27], v[24:25] neg_lo:[0,0,1] neg_hi:[0,0,1]
	v_pk_fma_f32 v[24:25], v[68:69], v[26:27], v[24:25] op_sel_hi:[1,0,1]
	v_mov_b32_e32 v26, v27
	v_mov_b32_e32 v24, v31
	v_mov_b32_e32 v59, v25
	v_pk_mul_f32 v[24:25], v[68:69], v[24:25] op_sel:[1,0] op_sel_hi:[0,0]
	v_pk_fma_f32 v[30:31], v[68:69], v[26:27], v[24:25] neg_lo:[0,0,1] neg_hi:[0,0,1]
	v_pk_fma_f32 v[24:25], v[68:69], v[54:55], v[24:25] op_sel_hi:[1,0,1]
	s_nop 0
	v_mov_b32_e32 v31, v25
	v_pk_mul_f32 v[24:25], v[68:69], v[20:21] op_sel:[1,0] op_sel_hi:[0,0]
	v_pk_fma_f32 v[60:61], v[68:69], v[16:17], v[24:25] neg_lo:[0,0,1] neg_hi:[0,0,1]
	v_pk_fma_f32 v[24:25], v[68:69], v[16:17], v[24:25] op_sel_hi:[1,0,1]
	v_pk_mul_f32 v[20:21], v[68:69], v[20:21] op_sel:[1,1] op_sel_hi:[0,1]
	v_mov_b32_e32 v24, v17
	v_pk_fma_f32 v[62:63], v[68:69], v[24:25], v[20:21] neg_lo:[0,0,1] neg_hi:[0,0,1]
	v_pk_fma_f32 v[16:17], v[68:69], v[16:17], v[20:21] op_sel:[0,1,0]
	v_mov_b32_e32 v20, v19
	v_mov_b32_e32 v63, v17
	v_pk_mul_f32 v[16:17], v[68:69], v[22:23] op_sel:[1,0] op_sel_hi:[0,0]
	v_pk_fma_f32 v[64:65], v[68:69], v[18:19], v[16:17] neg_lo:[0,0,1] neg_hi:[0,0,1]
	v_pk_fma_f32 v[16:17], v[68:69], v[18:19], v[16:17] op_sel_hi:[1,0,1]
	v_mov_b32_e32 v18, v19
	v_mov_b32_e32 v16, v23
	v_mov_b32_e32 v65, v17
	v_pk_mul_f32 v[16:17], v[68:69], v[16:17] op_sel:[1,0] op_sel_hi:[0,0]
	v_pk_fma_f32 v[66:67], v[68:69], v[18:19], v[16:17] neg_lo:[0,0,1] neg_hi:[0,0,1]
	v_pk_fma_f32 v[16:17], v[68:69], v[20:21], v[16:17] op_sel_hi:[1,0,1]
; template <bool FINAL>
; __device__ __forceinline__ void s5_wave(const Params& P, int j, int g, int idx0, int stride, char* ldsw) {
;     ...
;   float pr = lbr, pi = lbi;
; #pragma unroll
;   for (int s6 = 0; s6 < 6; ++s6) {
;     float nr2 = pr * pr - pi * pi, ni2 = 2.f * pr * pi;
;     pr = nr2; pi = ni2;
;   }
;     ...
;   for (int idx = idx0; idx < 16384; idx += stride) {
;   const int b = idx >> 11, chunk = ((idx >> 5) + 8 * b) & 63;
;   const size_t rowbase = (size_t)b * 4096 + chunk * 64;
;   const u16* up = Zo + (rowbase + lane) * 1280 + 768 + g * 16;
;   const uint4 u0 = *reinterpret_cast<const uint4*>(up);
;   const uint4 u1 = *reinterpret_cast<const uint4*>(up + 8);
	v_mov_b32_e32 v61, v25
	v_mul_f32_e32 v16, v55, v55
	v_fma_f32 v16, v52, v52, -v16
	v_mov_b32_e32 v67, v17
	v_add_f32_e32 v17, v52, v52
	v_mov_b32_e32 v54, v16
	v_pk_mul_f32 v[18:19], v[16:17], v[54:55]
	v_mov_b32_e32 v54, v55
	v_pk_mov_b32 v[16:17], v[18:19], v[16:17] op_sel:[1,0]
	v_mov_b32_e32 v182, v19
	v_pk_mul_f32 v[20:21], v[16:17], v[182:183]
	v_pk_fma_f32 v[16:17], v[16:17], v[182:183], v[18:19] neg_lo:[1,0,0] neg_hi:[1,0,0]
	v_pk_mul_f32 v[22:23], v[18:19], v[20:21]
	v_pk_mov_b32 v[18:19], v[18:19], v[16:17] op_sel:[1,0]
	v_mov_b32_e32 v182, v21
	v_pk_mul_f32 v[18:19], v[18:19], v[182:183]
	v_mov_b32_e32 v24, v16
	v_mov_b32_e32 v25, v23
	v_mov_b32_e32 v17, v19
	v_pk_mul_f32 v[16:17], v[24:25], v[16:17]
	v_pk_mul_f32 v[20:21], v[22:23], v[18:19]
	v_pk_fma_f32 v[18:19], v[22:23], v[18:19], v[16:17] op_sel:[1,0,0] neg_lo:[1,0,0] neg_hi:[1,0,0]
	v_pk_mul_f32 v[20:21], v[16:17], v[20:21]
	v_mov_b32_e32 v182, v18
	v_pk_mul_f32 v[22:23], v[18:19], v[182:183] op_sel_hi:[0,1]
	v_mov_b32_e32 v16, v21
	v_pk_fma_f32 v[18:19], v[18:19], v[182:183], v[16:17] op_sel_hi:[0,1,1] neg_lo:[0,0,1] neg_hi:[0,0,1]
	v_pk_mul_f32 v[16:17], v[22:23], v[16:17]
	v_mul_f32_e32 v20, v18, v18
	v_mov_b32_e32 v19, v17
	v_add_f32_e32 v16, v18, v18
	v_pk_fma_f32 v[18:19], v[18:19], v[18:19], v[20:21] op_sel_hi:[1,1,0] neg_lo:[1,0,0] neg_hi:[1,0,0]
	v_mov_b32_e32 v20, v17
	v_mov_b32_e32 v21, v19
	v_mov_b32_e32 v17, v19
	v_pk_mul_f32 v[16:17], v[20:21], v[16:17]
	v_mov_b32_e32 v20, v183
	v_pk_mov_b32 v[18:19], v[18:19], v[16:17] op_sel:[1,0]
	v_mov_b32_e32 v21, v16
	v_pk_mul_f32 v[22:23], v[18:19], v[20:21]
	v_pk_fma_f32 v[20:21], v[18:19], v[20:21], v[16:17] neg_lo:[1,0,0] neg_hi:[1,0,0]
	v_pk_mul_f32 v[22:23], v[16:17], v[22:23]
	v_lshl_add_u64 v[16:17], v[50:51], 2, s[0:1]
	global_load_dwordx4 v[16:19], v[16:17], off
	v_readlane_b32 s0, v251, 60
	v_mov_b32_e32 v69, v21
	v_mov_b32_e32 v72, v21
	v_lshl_add_u32 v24, v50, 2, s0
	v_lshl_add_u32 v91, v48, 2, s0
	v_readlane_b32 s0, v252, 11
	v_readlane_b32 s1, v252, 12
	v_mov_b32_e32 v73, v21
	v_pk_mov_b32 v[76:77], v[20:21], v[22:23] op_sel:[1,0]
	v_lshl_add_u64 v[70:71], v[50:51], 1, s[0:1]
	v_readlane_b32 s0, v253, 52
	v_lshlrev_b64 v[20:21], 3, v[48:49]
	v_readlane_b32 s1, v253, 53
	v_mul_u32_u24_e32 v25, 0x110, v90
	v_mov_b32_e32 v68, v22
	v_lshl_add_u64 v[78:79], s[0:1], 0, v[20:21]
	v_readlane_b32 s0, v253, 54
	v_readlane_b32 s1, v253, 55
	v_mov_b32_e32 v74, v22
	v_mov_b32_e32 v75, v22
	v_lshl_add_u64 v[80:81], s[0:1], 0, v[20:21]
	v_readlane_b32 s0, v251, 22
	v_add_u32_e32 v92, v24, v25
	s_mov_b32 s2, s0
	v_readlane_b32 s1, v251, 23
	v_and_b32_e32 v109, 31, v48
	v_mul_u32_u24_e32 v110, 0xa00, v109
	v_mov_b32_e32 v111, 0
	v_cmp_gt_u32_e32 vcc, 32, v48
	s_nop 1
	v_cndmask_b32_e64 v108, 0, 16, vcc
	v_permlane32_swap_b32_e32 v56, v44
	v_permlane32_swap_b32_e32 v57, v45
	v_permlane32_swap_b32_e32 v40, v42
	v_permlane32_swap_b32_e32 v41, v43
	v_permlane32_swap_b32_e32 v46, v36
	v_permlane32_swap_b32_e32 v47, v37
	v_permlane32_swap_b32_e32 v32, v34
	v_permlane32_swap_b32_e32 v33, v35
	v_permlane32_swap_b32_e32 v38, v28
	v_permlane32_swap_b32_e32 v39, v29
	v_permlane32_swap_b32_e32 v58, v30
	v_permlane32_swap_b32_e32 v59, v31
	v_permlane32_swap_b32_e32 v60, v62
	v_permlane32_swap_b32_e32 v61, v63
	v_permlane32_swap_b32_e32 v64, v66
	v_permlane32_swap_b32_e32 v65, v67
.LBB0_430:
	s_ashr_i32 s4, s2, 11
	s_lshr_b32 s0, s2, 5
	s_lshl_b32 s1, s4, 3
	s_add_i32 s1, s1, s0
	s_and_b32 s6, s1, 63
	s_ashr_i32 s5, s4, 31
	s_lshl_b64 s[0:1], s[4:5], 12
	s_lshl_b32 s5, s6, 6
	v_readlane_b32 s8, v253, 46
	s_or_b32 s0, s0, s5
	v_readlane_b32 s9, v253, 47
	s_lshl_b32 s4, s4, 6
	s_nop 0
	s_mul_i32 s7, s0, 0xa00
	s_add_u32 s10, s8, s7
	s_addc_u32 s11, s9, 0
	v_lshl_add_u64 v[234:235], v[110:111], 0, s[10:11]
	global_load_dwordx4 v[194:197], v[234:235], off offset:1536
	global_load_dwordx4 v[198:201], v[234:235], off offset:1552
	s_add_u32 s10, s10, 0x14000
	s_addc_u32 s11, s11, 0
	v_lshl_add_u64 v[234:235], v[110:111], 0, s[10:11]
	global_load_dwordx4 v[202:205], v[234:235], off offset:1536
	global_load_dwordx4 v[242:245], v[234:235], off offset:1552
	s_ashr_i32 s5, s4, 31
	s_lshl_b64 s[4:5], s[4:5], 14
	s_cmp_lt_u32 s6, 8
	s_cbranch_scc1 .LBB0_434
	v_mov_b32_e32 v82, 0
	v_lshl_add_u64 v[84:85], v[78:79], 0, s[4:5]
	s_mov_b32 s94, 0
	v_mov_b32_e32 v83, v82

; template <bool FINAL>
; __device__ __forceinline__ void s5_wave(const Params& P, int j, int g, int idx0, int stride, char* ldsw) {
;     ...
; #pragma unroll 2
;   for (int t = 0; t < 64; ++t) {
;     uint32_t w[8];
;     w[0] = __builtin_amdgcn_readlane(u0.x, t); w[1] = __builtin_amdgcn_readlane(u0.y, t);
;     w[2] = __builtin_amdgcn_readlane(u0.z, t); w[3] = __builtin_amdgcn_readlane(u0.w, t);
;     w[4] = __builtin_amdgcn_readlane(u1.x, t); w[5] = __builtin_amdgcn_readlane(u1.y, t);
;     w[6] = __builtin_amdgcn_readlane(u1.z, t); w[7] = __builtin_amdgcn_readlane(u1.w, t);
;     f32x2 acc0 = (f32x2){lbr * hr - lbi * hi, lbr * hi + lbi * hr}, acc1 = (f32x2){0.f, 0.f};
; #pragma unroll
;     for (int q = 0; q < 8; ++q) {
;       float ua = __uint_as_float(w[q] << 16), ub = __uint_as_float(w[q] & 0xffff0000u);
;       acc0 = bb[2 * q] * (f32x2){ua, ua} + acc0;
;       acc1 = bb[2 * q + 1] * (f32x2){ub, ub} + acc1;
;     }
;     acc0 = acc0 + acc1;
;     hr = acc0.x; hi = acc0.y;
;     if (FINAL) hbuf[t * 68 + p] = pack2(hr, hi);
;   }
.LBB0_437:
	s_waitcnt vmcnt(0)
	v_lshlrev_b32_e32 v100, v108, v194
	v_lshlrev_b32_e32 v101, v108, v195
	v_lshlrev_b32_e32 v102, v108, v196
	v_lshlrev_b32_e32 v103, v108, v197
	v_lshlrev_b32_e32 v104, v108, v198
	v_lshlrev_b32_e32 v105, v108, v199
	v_lshlrev_b32_e32 v106, v108, v200
	v_lshlrev_b32_e32 v107, v108, v201
	v_and_b32_e32 v100, 0xffff0000, v100
	v_and_b32_e32 v101, 0xffff0000, v101
	v_and_b32_e32 v102, 0xffff0000, v102
	v_and_b32_e32 v103, 0xffff0000, v103
	v_and_b32_e32 v104, 0xffff0000, v104
	v_and_b32_e32 v105, 0xffff0000, v105
	v_and_b32_e32 v106, 0xffff0000, v106
	v_and_b32_e32 v107, 0xffff0000, v107
	v_mfma_f32_32x32x2_f32 v[116:131], v100, v56, 0
	v_mfma_f32_32x32x2_f32 v[132:147], v100, v57, 0
	v_mfma_f32_32x32x2_f32 v[148:163], v100, v44, 0
	v_mfma_f32_32x32x2_f32 v[164:179], v100, v45, 0
	v_mfma_f32_32x32x2_f32 v[116:131], v101, v40, v[116:131]
	v_mfma_f32_32x32x2_f32 v[132:147], v101, v41, v[132:147]
	v_mfma_f32_32x32x2_f32 v[148:163], v101, v42, v[148:163]
	v_mfma_f32_32x32x2_f32 v[164:179], v101, v43, v[164:179]
	v_mfma_f32_32x32x2_f32 v[116:131], v102, v46, v[116:131]
	v_mfma_f32_32x32x2_f32 v[132:147], v102, v47, v[132:147]
	v_mfma_f32_32x32x2_f32 v[148:163], v102, v36, v[148:163]
	v_mfma_f32_32x32x2_f32 v[164:179], v102, v37, v[164:179]
	v_mfma_f32_32x32x2_f32 v[116:131], v103, v32, v[116:131]
	v_mfma_f32_32x32x2_f32 v[132:147], v103, v33, v[132:147]
	v_mfma_f32_32x32x2_f32 v[148:163], v103, v34, v[148:163]
	v_mfma_f32_32x32x2_f32 v[164:179], v103, v35, v[164:179]
	v_mfma_f32_32x32x2_f32 v[116:131], v104, v38, v[116:131]
	v_mfma_f32_32x32x2_f32 v[132:147], v104, v39, v[132:147]
	v_mfma_f32_32x32x2_f32 v[148:163], v104, v28, v[148:163]
	v_mfma_f32_32x32x2_f32 v[164:179], v104, v29, v[164:179]
	v_mfma_f32_32x32x2_f32 v[116:131], v105, v58, v[116:131]
	v_mfma_f32_32x32x2_f32 v[132:147], v105, v59, v[132:147]
	v_mfma_f32_32x32x2_f32 v[148:163], v105, v30, v[148:163]
	v_mfma_f32_32x32x2_f32 v[164:179], v105, v31, v[164:179]
	v_mfma_f32_32x32x2_f32 v[116:131], v106, v60, v[116:131]
	v_mfma_f32_32x32x2_f32 v[132:147], v106, v61, v[132:147]
	v_mfma_f32_32x32x2_f32 v[148:163], v106, v62, v[148:163]
	v_mfma_f32_32x32x2_f32 v[164:179], v106, v63, v[164:179]
	v_mfma_f32_32x32x2_f32 v[116:131], v107, v64, v[116:131]
	v_mfma_f32_32x32x2_f32 v[132:147], v107, v65, v[132:147]
	v_mfma_f32_32x32x2_f32 v[148:163], v107, v66, v[148:163]
	v_mfma_f32_32x32x2_f32 v[164:179], v107, v67, v[164:179]
	s_nop 15
	s_nop 3
	v_permlane32_swap_b32_e32 v116, v148
	v_permlane32_swap_b32_e32 v132, v164
	v_permlane32_swap_b32_e32 v117, v149
	v_permlane32_swap_b32_e32 v133, v165
	v_permlane32_swap_b32_e32 v118, v150
	v_permlane32_swap_b32_e32 v134, v166
	v_permlane32_swap_b32_e32 v119, v151
	v_permlane32_swap_b32_e32 v135, v167
	v_permlane32_swap_b32_e32 v120, v152
	v_permlane32_swap_b32_e32 v136, v168
	v_permlane32_swap_b32_e32 v121, v153
	v_permlane32_swap_b32_e32 v137, v169
	v_permlane32_swap_b32_e32 v122, v154
	v_permlane32_swap_b32_e32 v138, v170
	v_permlane32_swap_b32_e32 v123, v155
	v_permlane32_swap_b32_e32 v139, v171
	v_permlane32_swap_b32_e32 v124, v156
	v_permlane32_swap_b32_e32 v140, v172
	v_permlane32_swap_b32_e32 v125, v157
	v_permlane32_swap_b32_e32 v141, v173
	v_permlane32_swap_b32_e32 v126, v158
	v_permlane32_swap_b32_e32 v142, v174
	v_permlane32_swap_b32_e32 v127, v159
	v_permlane32_swap_b32_e32 v143, v175
	v_permlane32_swap_b32_e32 v128, v160
	v_permlane32_swap_b32_e32 v144, v176
	v_permlane32_swap_b32_e32 v129, v161
	v_permlane32_swap_b32_e32 v145, v177
	v_permlane32_swap_b32_e32 v130, v162
	v_permlane32_swap_b32_e32 v146, v178
	v_permlane32_swap_b32_e32 v131, v163
	v_permlane32_swap_b32_e32 v147, v179
	v_fma_f32 v116, v52, v82, v116
	v_fma_f32 v132, v52, v83, v132
	v_fma_f32 v116, -v54, v83, v116
	v_fma_f32 v132, v54, v82, v132
	v_cvt_pk_bf16_f32 v109, v116, v132
	ds_write_b32 v91, v109 offset:0
	v_fma_f32 v117, v52, v116, v117
	v_fma_f32 v133, v52, v132, v133
	v_fma_f32 v117, -v54, v132, v117
	v_fma_f32 v133, v54, v116, v133
	v_cvt_pk_bf16_f32 v114, v117, v133
	ds_write_b32 v91, v114 offset:272
	v_fma_f32 v118, v52, v117, v118
	v_fma_f32 v134, v52, v133, v134
	v_fma_f32 v118, -v54, v133, v118
	v_fma_f32 v134, v54, v117, v134
	v_cvt_pk_bf16_f32 v109, v118, v134
	ds_write_b32 v91, v109 offset:544
	v_fma_f32 v119, v52, v118, v119
	v_fma_f32 v135, v52, v134, v135
	v_fma_f32 v119, -v54, v134, v119
	v_fma_f32 v135, v54, v118, v135
	v_cvt_pk_bf16_f32 v114, v119, v135
	ds_write_b32 v91, v114 offset:816
	v_fma_f32 v148, v52, v119, v148
	v_fma_f32 v164, v52, v135, v164
	v_fma_f32 v148, -v54, v135, v148
	v_fma_f32 v164, v54, v119, v164
	v_cvt_pk_bf16_f32 v109, v148, v164
	ds_write_b32 v91, v109 offset:1088
	v_fma_f32 v149, v52, v148, v149
	v_fma_f32 v165, v52, v164, v165
	v_fma_f32 v149, -v54, v164, v149
	v_fma_f32 v165, v54, v148, v165
	v_cvt_pk_bf16_f32 v114, v149, v165
	ds_write_b32 v91, v114 offset:1360
	v_fma_f32 v150, v52, v149, v150
	v_fma_f32 v166, v52, v165, v166
	v_fma_f32 v150, -v54, v165, v150
	v_fma_f32 v166, v54, v149, v166
	v_cvt_pk_bf16_f32 v109, v150, v166
	ds_write_b32 v91, v109 offset:1632
	v_fma_f32 v151, v52, v150, v151
	v_fma_f32 v167, v52, v166, v167
	v_fma_f32 v151, -v54, v166, v151
	v_fma_f32 v167, v54, v150, v167
	v_cvt_pk_bf16_f32 v114, v151, v167
	ds_write_b32 v91, v114 offset:1904
	v_fma_f32 v120, v52, v151, v120
	v_fma_f32 v136, v52, v167, v136
	v_fma_f32 v120, -v54, v167, v120
	v_fma_f32 v136, v54, v151, v136
	v_cvt_pk_bf16_f32 v109, v120, v136
	ds_write_b32 v91, v109 offset:2176
	v_fma_f32 v121, v52, v120, v121
	v_fma_f32 v137, v52, v136, v137
	v_fma_f32 v121, -v54, v136, v121
	v_fma_f32 v137, v54, v120, v137
; template <bool FINAL>
; __device__ __forceinline__ void s5_wave(const Params& P, int j, int g, int idx0, int stride, char* ldsw) {
;     ...
; #pragma unroll 2
;   for (int t = 0; t < 64; ++t) {
;     uint32_t w[8];
;     w[0] = __builtin_amdgcn_readlane(u0.x, t); w[1] = __builtin_amdgcn_readlane(u0.y, t);
;     w[2] = __builtin_amdgcn_readlane(u0.z, t); w[3] = __builtin_amdgcn_readlane(u0.w, t);
;     w[4] = __builtin_amdgcn_readlane(u1.x, t); w[5] = __builtin_amdgcn_readlane(u1.y, t);
;     w[6] = __builtin_amdgcn_readlane(u1.z, t); w[7] = __builtin_amdgcn_readlane(u1.w, t);
;     f32x2 acc0 = (f32x2){lbr * hr - lbi * hi, lbr * hi + lbi * hr}, acc1 = (f32x2){0.f, 0.f};
; #pragma unroll
;     for (int q = 0; q < 8; ++q) {
;       float ua = __uint_as_float(w[q] << 16), ub = __uint_as_float(w[q] & 0xffff0000u);
;       acc0 = bb[2 * q] * (f32x2){ua, ua} + acc0;
;       acc1 = bb[2 * q + 1] * (f32x2){ub, ub} + acc1;
;     }
;     acc0 = acc0 + acc1;
;     hr = acc0.x; hi = acc0.y;
;     if (FINAL) hbuf[t * 68 + p] = pack2(hr, hi);
;   }
	v_cvt_pk_bf16_f32 v114, v121, v137
	ds_write_b32 v91, v114 offset:2448
	v_fma_f32 v122, v52, v121, v122
	v_fma_f32 v138, v52, v137, v138
	v_fma_f32 v122, -v54, v137, v122
	v_fma_f32 v138, v54, v121, v138
	v_cvt_pk_bf16_f32 v109, v122, v138
	ds_write_b32 v91, v109 offset:2720
	v_fma_f32 v123, v52, v122, v123
	v_fma_f32 v139, v52, v138, v139
	v_fma_f32 v123, -v54, v138, v123
	v_fma_f32 v139, v54, v122, v139
	v_cvt_pk_bf16_f32 v114, v123, v139
	ds_write_b32 v91, v114 offset:2992
	v_fma_f32 v152, v52, v123, v152
	v_fma_f32 v168, v52, v139, v168
	v_fma_f32 v152, -v54, v139, v152
	v_fma_f32 v168, v54, v123, v168
	v_cvt_pk_bf16_f32 v109, v152, v168
	ds_write_b32 v91, v109 offset:3264
	v_fma_f32 v153, v52, v152, v153
	v_fma_f32 v169, v52, v168, v169
	v_fma_f32 v153, -v54, v168, v153
	v_fma_f32 v169, v54, v152, v169
	v_cvt_pk_bf16_f32 v114, v153, v169
	ds_write_b32 v91, v114 offset:3536
	v_fma_f32 v154, v52, v153, v154
	v_fma_f32 v170, v52, v169, v170
	v_fma_f32 v154, -v54, v169, v154
	v_fma_f32 v170, v54, v153, v170
	v_cvt_pk_bf16_f32 v109, v154, v170
	ds_write_b32 v91, v109 offset:3808
	v_fma_f32 v155, v52, v154, v155
	v_fma_f32 v171, v52, v170, v171
	v_fma_f32 v155, -v54, v170, v155
	v_fma_f32 v171, v54, v154, v171
	v_cvt_pk_bf16_f32 v114, v155, v171
	ds_write_b32 v91, v114 offset:4080
	v_fma_f32 v124, v52, v155, v124
	v_fma_f32 v140, v52, v171, v140
	v_fma_f32 v124, -v54, v171, v124
	v_fma_f32 v140, v54, v155, v140
	v_cvt_pk_bf16_f32 v109, v124, v140
	ds_write_b32 v91, v109 offset:4352
	v_fma_f32 v125, v52, v124, v125
	v_fma_f32 v141, v52, v140, v141
	v_fma_f32 v125, -v54, v140, v125
	v_fma_f32 v141, v54, v124, v141
	v_cvt_pk_bf16_f32 v114, v125, v141
	ds_write_b32 v91, v114 offset:4624
	v_fma_f32 v126, v52, v125, v126
	v_fma_f32 v142, v52, v141, v142
	v_fma_f32 v126, -v54, v141, v126
	v_fma_f32 v142, v54, v125, v142
	v_cvt_pk_bf16_f32 v109, v126, v142
	ds_write_b32 v91, v109 offset:4896
	v_fma_f32 v127, v52, v126, v127
	v_fma_f32 v143, v52, v142, v143
	v_fma_f32 v127, -v54, v142, v127
	v_fma_f32 v143, v54, v126, v143
	v_cvt_pk_bf16_f32 v114, v127, v143
	ds_write_b32 v91, v114 offset:5168
	v_fma_f32 v156, v52, v127, v156
	v_fma_f32 v172, v52, v143, v172
	v_fma_f32 v156, -v54, v143, v156
	v_fma_f32 v172, v54, v127, v172
	v_cvt_pk_bf16_f32 v109, v156, v172
	ds_write_b32 v91, v109 offset:5440
	v_fma_f32 v157, v52, v156, v157
	v_fma_f32 v173, v52, v172, v173
	v_fma_f32 v157, -v54, v172, v157
	v_fma_f32 v173, v54, v156, v173
	v_cvt_pk_bf16_f32 v114, v157, v173
	ds_write_b32 v91, v114 offset:5712
	v_fma_f32 v158, v52, v157, v158
	v_fma_f32 v174, v52, v173, v174
	v_fma_f32 v158, -v54, v173, v158
	v_fma_f32 v174, v54, v157, v174
	v_cvt_pk_bf16_f32 v109, v158, v174
	ds_write_b32 v91, v109 offset:5984
	v_fma_f32 v159, v52, v158, v159
	v_fma_f32 v175, v52, v174, v175
	v_fma_f32 v159, -v54, v174, v159
	v_fma_f32 v175, v54, v158, v175
	v_cvt_pk_bf16_f32 v114, v159, v175
	ds_write_b32 v91, v114 offset:6256
	v_fma_f32 v128, v52, v159, v128
	v_fma_f32 v144, v52, v175, v144
	v_fma_f32 v128, -v54, v175, v128
	v_fma_f32 v144, v54, v159, v144
	v_cvt_pk_bf16_f32 v109, v128, v144
	ds_write_b32 v91, v109 offset:6528
	v_fma_f32 v129, v52, v128, v129
	v_fma_f32 v145, v52, v144, v145
	v_fma_f32 v129, -v54, v144, v129
	v_fma_f32 v145, v54, v128, v145
	v_cvt_pk_bf16_f32 v114, v129, v145
	ds_write_b32 v91, v114 offset:6800
	v_fma_f32 v130, v52, v129, v130
	v_fma_f32 v146, v52, v145, v146
	v_fma_f32 v130, -v54, v145, v130
	v_fma_f32 v146, v54, v129, v146
	v_cvt_pk_bf16_f32 v109, v130, v146
	ds_write_b32 v91, v109 offset:7072
	v_fma_f32 v131, v52, v130, v131
	v_fma_f32 v147, v52, v146, v147
	v_fma_f32 v131, -v54, v146, v131
	v_fma_f32 v147, v54, v130, v147
	v_cvt_pk_bf16_f32 v114, v131, v147
	ds_write_b32 v91, v114 offset:7344
	v_fma_f32 v160, v52, v131, v160
	v_fma_f32 v176, v52, v147, v176
	v_fma_f32 v160, -v54, v147, v160
	v_fma_f32 v176, v54, v131, v176
	v_cvt_pk_bf16_f32 v109, v160, v176
	ds_write_b32 v91, v109 offset:7616
	v_fma_f32 v161, v52, v160, v161
	v_fma_f32 v177, v52, v176, v177
	v_fma_f32 v161, -v54, v176, v161
	v_fma_f32 v177, v54, v160, v177
	v_cvt_pk_bf16_f32 v114, v161, v177
	ds_write_b32 v91, v114 offset:7888
	v_fma_f32 v162, v52, v161, v162
	v_fma_f32 v178, v52, v177, v178
	v_fma_f32 v162, -v54, v177, v162
	v_fma_f32 v178, v54, v161, v178
	v_cvt_pk_bf16_f32 v109, v162, v178
	ds_write_b32 v91, v109 offset:8160
	v_fma_f32 v163, v52, v162, v163
	v_fma_f32 v179, v52, v178, v179
	v_fma_f32 v163, -v54, v178, v163
	v_fma_f32 v179, v54, v162, v179
	v_cvt_pk_bf16_f32 v114, v163, v179
	ds_write_b32 v91, v114 offset:8432
	v_mov_b32_e32 v82, v163
	v_mov_b32_e32 v83, v179
	v_lshlrev_b32_e32 v100, v108, v202
	v_lshlrev_b32_e32 v101, v108, v203
	v_lshlrev_b32_e32 v102, v108, v204
	v_lshlrev_b32_e32 v103, v108, v205
	v_lshlrev_b32_e32 v104, v108, v242
	v_lshlrev_b32_e32 v105, v108, v243
	v_lshlrev_b32_e32 v106, v108, v244
	v_lshlrev_b32_e32 v107, v108, v245
	v_and_b32_e32 v100, 0xffff0000, v100
	v_and_b32_e32 v101, 0xffff0000, v101
	v_and_b32_e32 v102, 0xffff0000, v102
	v_and_b32_e32 v103, 0xffff0000, v103
	v_and_b32_e32 v104, 0xffff0000, v104
	v_and_b32_e32 v105, 0xffff0000, v105
	v_and_b32_e32 v106, 0xffff0000, v106
	v_and_b32_e32 v107, 0xffff0000, v107
	v_mfma_f32_32x32x2_f32 v[116:131], v100, v56, 0
	v_mfma_f32_32x32x2_f32 v[132:147], v100, v57, 0
	v_mfma_f32_32x32x2_f32 v[148:163], v100, v44, 0
	v_mfma_f32_32x32x2_f32 v[164:179], v100, v45, 0
	v_mfma_f32_32x32x2_f32 v[116:131], v101, v40, v[116:131]
	v_mfma_f32_32x32x2_f32 v[132:147], v101, v41, v[132:147]
	v_mfma_f32_32x32x2_f32 v[148:163], v101, v42, v[148:163]
	v_mfma_f32_32x32x2_f32 v[164:179], v101, v43, v[164:179]
; template <bool FINAL>
; __device__ __forceinline__ void s5_wave(const Params& P, int j, int g, int idx0, int stride, char* ldsw) {
;     ...
; #pragma unroll 2
;   for (int t = 0; t < 64; ++t) {
;     uint32_t w[8];
;     w[0] = __builtin_amdgcn_readlane(u0.x, t); w[1] = __builtin_amdgcn_readlane(u0.y, t);
;     w[2] = __builtin_amdgcn_readlane(u0.z, t); w[3] = __builtin_amdgcn_readlane(u0.w, t);
;     w[4] = __builtin_amdgcn_readlane(u1.x, t); w[5] = __builtin_amdgcn_readlane(u1.y, t);
;     w[6] = __builtin_amdgcn_readlane(u1.z, t); w[7] = __builtin_amdgcn_readlane(u1.w, t);
;     f32x2 acc0 = (f32x2){lbr * hr - lbi * hi, lbr * hi + lbi * hr}, acc1 = (f32x2){0.f, 0.f};
; #pragma unroll
;     for (int q = 0; q < 8; ++q) {
;       float ua = __uint_as_float(w[q] << 16), ub = __uint_as_float(w[q] & 0xffff0000u);
;       acc0 = bb[2 * q] * (f32x2){ua, ua} + acc0;
;       acc1 = bb[2 * q + 1] * (f32x2){ub, ub} + acc1;
;     }
;     acc0 = acc0 + acc1;
;     hr = acc0.x; hi = acc0.y;
;     if (FINAL) hbuf[t * 68 + p] = pack2(hr, hi);
;   }
	v_mfma_f32_32x32x2_f32 v[116:131], v102, v46, v[116:131]
	v_mfma_f32_32x32x2_f32 v[132:147], v102, v47, v[132:147]
	v_mfma_f32_32x32x2_f32 v[148:163], v102, v36, v[148:163]
	v_mfma_f32_32x32x2_f32 v[164:179], v102, v37, v[164:179]
	v_mfma_f32_32x32x2_f32 v[116:131], v103, v32, v[116:131]
	v_mfma_f32_32x32x2_f32 v[132:147], v103, v33, v[132:147]
	v_mfma_f32_32x32x2_f32 v[148:163], v103, v34, v[148:163]
	v_mfma_f32_32x32x2_f32 v[164:179], v103, v35, v[164:179]
	v_mfma_f32_32x32x2_f32 v[116:131], v104, v38, v[116:131]
	v_mfma_f32_32x32x2_f32 v[132:147], v104, v39, v[132:147]
	v_mfma_f32_32x32x2_f32 v[148:163], v104, v28, v[148:163]
	v_mfma_f32_32x32x2_f32 v[164:179], v104, v29, v[164:179]
	v_mfma_f32_32x32x2_f32 v[116:131], v105, v58, v[116:131]
	v_mfma_f32_32x32x2_f32 v[132:147], v105, v59, v[132:147]
	v_mfma_f32_32x32x2_f32 v[148:163], v105, v30, v[148:163]
	v_mfma_f32_32x32x2_f32 v[164:179], v105, v31, v[164:179]
	v_mfma_f32_32x32x2_f32 v[116:131], v106, v60, v[116:131]
	v_mfma_f32_32x32x2_f32 v[132:147], v106, v61, v[132:147]
	v_mfma_f32_32x32x2_f32 v[148:163], v106, v62, v[148:163]
	v_mfma_f32_32x32x2_f32 v[164:179], v106, v63, v[164:179]
	v_mfma_f32_32x32x2_f32 v[116:131], v107, v64, v[116:131]
	v_mfma_f32_32x32x2_f32 v[132:147], v107, v65, v[132:147]
	v_mfma_f32_32x32x2_f32 v[148:163], v107, v66, v[148:163]
	v_mfma_f32_32x32x2_f32 v[164:179], v107, v67, v[164:179]
	s_nop 15
	s_nop 3
	v_permlane32_swap_b32_e32 v116, v148
	v_permlane32_swap_b32_e32 v132, v164
	v_permlane32_swap_b32_e32 v117, v149
	v_permlane32_swap_b32_e32 v133, v165
	v_permlane32_swap_b32_e32 v118, v150
	v_permlane32_swap_b32_e32 v134, v166
	v_permlane32_swap_b32_e32 v119, v151
	v_permlane32_swap_b32_e32 v135, v167
	v_permlane32_swap_b32_e32 v120, v152
	v_permlane32_swap_b32_e32 v136, v168
	v_permlane32_swap_b32_e32 v121, v153
	v_permlane32_swap_b32_e32 v137, v169
	v_permlane32_swap_b32_e32 v122, v154
	v_permlane32_swap_b32_e32 v138, v170
	v_permlane32_swap_b32_e32 v123, v155
	v_permlane32_swap_b32_e32 v139, v171
	v_permlane32_swap_b32_e32 v124, v156
	v_permlane32_swap_b32_e32 v140, v172
	v_permlane32_swap_b32_e32 v125, v157
	v_permlane32_swap_b32_e32 v141, v173
	v_permlane32_swap_b32_e32 v126, v158
	v_permlane32_swap_b32_e32 v142, v174
	v_permlane32_swap_b32_e32 v127, v159
	v_permlane32_swap_b32_e32 v143, v175
	v_permlane32_swap_b32_e32 v128, v160
	v_permlane32_swap_b32_e32 v144, v176
	v_permlane32_swap_b32_e32 v129, v161
	v_permlane32_swap_b32_e32 v145, v177
	v_permlane32_swap_b32_e32 v130, v162
	v_permlane32_swap_b32_e32 v146, v178
	v_permlane32_swap_b32_e32 v131, v163
	v_permlane32_swap_b32_e32 v147, v179
	v_fma_f32 v116, v52, v82, v116
	v_fma_f32 v132, v52, v83, v132
	v_fma_f32 v116, -v54, v83, v116
	v_fma_f32 v132, v54, v82, v132
	v_cvt_pk_bf16_f32 v109, v116, v132
	ds_write_b32 v91, v109 offset:8704
	v_fma_f32 v117, v52, v116, v117
	v_fma_f32 v133, v52, v132, v133
	v_fma_f32 v117, -v54, v132, v117
	v_fma_f32 v133, v54, v116, v133
	v_cvt_pk_bf16_f32 v114, v117, v133
	ds_write_b32 v91, v114 offset:8976
	v_fma_f32 v118, v52, v117, v118
	v_fma_f32 v134, v52, v133, v134
	v_fma_f32 v118, -v54, v133, v118
	v_fma_f32 v134, v54, v117, v134
	v_cvt_pk_bf16_f32 v109, v118, v134
	ds_write_b32 v91, v109 offset:9248
	v_fma_f32 v119, v52, v118, v119
	v_fma_f32 v135, v52, v134, v135
	v_fma_f32 v119, -v54, v134, v119
	v_fma_f32 v135, v54, v118, v135
	v_cvt_pk_bf16_f32 v114, v119, v135
	ds_write_b32 v91, v114 offset:9520
	v_fma_f32 v148, v52, v119, v148
	v_fma_f32 v164, v52, v135, v164
	v_fma_f32 v148, -v54, v135, v148
	v_fma_f32 v164, v54, v119, v164
	v_cvt_pk_bf16_f32 v109, v148, v164
	ds_write_b32 v91, v109 offset:9792
	v_fma_f32 v149, v52, v148, v149
	v_fma_f32 v165, v52, v164, v165
	v_fma_f32 v149, -v54, v164, v149
	v_fma_f32 v165, v54, v148, v165
	v_cvt_pk_bf16_f32 v114, v149, v165
	ds_write_b32 v91, v114 offset:10064
	v_fma_f32 v150, v52, v149, v150
	v_fma_f32 v166, v52, v165, v166
	v_fma_f32 v150, -v54, v165, v150
	v_fma_f32 v166, v54, v149, v166
	v_cvt_pk_bf16_f32 v109, v150, v166
	ds_write_b32 v91, v109 offset:10336
	v_fma_f32 v151, v52, v150, v151
	v_fma_f32 v167, v52, v166, v167
	v_fma_f32 v151, -v54, v166, v151
	v_fma_f32 v167, v54, v150, v167
	v_cvt_pk_bf16_f32 v114, v151, v167
	ds_write_b32 v91, v114 offset:10608
	v_fma_f32 v120, v52, v151, v120
	v_fma_f32 v136, v52, v167, v136
	v_fma_f32 v120, -v54, v167, v120
	v_fma_f32 v136, v54, v151, v136
	v_cvt_pk_bf16_f32 v109, v120, v136
	ds_write_b32 v91, v109 offset:10880
	v_fma_f32 v121, v52, v120, v121
	v_fma_f32 v137, v52, v136, v137
	v_fma_f32 v121, -v54, v136, v121
	v_fma_f32 v137, v54, v120, v137
	v_cvt_pk_bf16_f32 v114, v121, v137
	ds_write_b32 v91, v114 offset:11152
	v_fma_f32 v122, v52, v121, v122
	v_fma_f32 v138, v52, v137, v138
	v_fma_f32 v122, -v54, v137, v122
	v_fma_f32 v138, v54, v121, v138
	v_cvt_pk_bf16_f32 v109, v122, v138
	ds_write_b32 v91, v109 offset:11424
	v_fma_f32 v123, v52, v122, v123
	v_fma_f32 v139, v52, v138, v139
	v_fma_f32 v123, -v54, v138, v123
	v_fma_f32 v139, v54, v122, v139
	v_cvt_pk_bf16_f32 v114, v123, v139
	ds_write_b32 v91, v114 offset:11696
	v_fma_f32 v152, v52, v123, v152
	v_fma_f32 v168, v52, v139, v168
	v_fma_f32 v152, -v54, v139, v152
	v_fma_f32 v168, v54, v123, v168
	v_cvt_pk_bf16_f32 v109, v152, v168
	ds_write_b32 v91, v109 offset:11968
	v_fma_f32 v153, v52, v152, v153
	v_fma_f32 v169, v52, v168, v169
	v_fma_f32 v153, -v54, v168, v153
	v_fma_f32 v169, v54, v152, v169
	v_cvt_pk_bf16_f32 v114, v153, v169
	ds_write_b32 v91, v114 offset:12240
	v_fma_f32 v154, v52, v153, v154
	v_fma_f32 v170, v52, v169, v170
	v_fma_f32 v154, -v54, v169, v154
	v_fma_f32 v170, v54, v153, v170
; template <bool FINAL>
; __device__ __forceinline__ void s5_wave(const Params& P, int j, int g, int idx0, int stride, char* ldsw) {
;     ...
; #pragma unroll 2
;   for (int t = 0; t < 64; ++t) {
;     uint32_t w[8];
;     w[0] = __builtin_amdgcn_readlane(u0.x, t); w[1] = __builtin_amdgcn_readlane(u0.y, t);
;     w[2] = __builtin_amdgcn_readlane(u0.z, t); w[3] = __builtin_amdgcn_readlane(u0.w, t);
;     w[4] = __builtin_amdgcn_readlane(u1.x, t); w[5] = __builtin_amdgcn_readlane(u1.y, t);
;     w[6] = __builtin_amdgcn_readlane(u1.z, t); w[7] = __builtin_amdgcn_readlane(u1.w, t);
;     f32x2 acc0 = (f32x2){lbr * hr - lbi * hi, lbr * hi + lbi * hr}, acc1 = (f32x2){0.f, 0.f};
; #pragma unroll
;     for (int q = 0; q < 8; ++q) {
;       float ua = __uint_as_float(w[q] << 16), ub = __uint_as_float(w[q] & 0xffff0000u);
;       acc0 = bb[2 * q] * (f32x2){ua, ua} + acc0;
;       acc1 = bb[2 * q + 1] * (f32x2){ub, ub} + acc1;
;     }
;     acc0 = acc0 + acc1;
;     hr = acc0.x; hi = acc0.y;
;     if (FINAL) hbuf[t * 68 + p] = pack2(hr, hi);
;   }
;     ...
;     u16* zs = reinterpret_cast<u16*>(P.ws + OFF_BIG + (size_t)T * 1280 * 2);
;     uint2 uw[4];
; #pragma unroll
;     for (int mt = 0; mt < 4; ++mt)
;       uw[mt] = *reinterpret_cast<const uint2*>(Zo + (rowbase + mt * 16 + fr) * 1280 + 768 + g * 16 + 4 * fq);
; #pragma unroll
;     for (int mt = 0; mt < 4; ++mt) {
;       f32x4 y = {0.f, 0.f, 0.f, 0.f};
; #pragma unroll
;       for (int ks = 0; ks < 4; ++ks) {
;         bf16x8 a = *reinterpret_cast<const bf16x8*>(hbuf + (mt * 16 + fr) * 68 + ks * 16 + fq * 4);
;         y = __builtin_amdgcn_mfma_f32_16x16x32_bf16(bc[ks], a, y, 0, 0, 0);
;       }
	v_cvt_pk_bf16_f32 v109, v154, v170
	ds_write_b32 v91, v109 offset:12512
	v_fma_f32 v155, v52, v154, v155
	v_fma_f32 v171, v52, v170, v171
	v_fma_f32 v155, -v54, v170, v155
	v_fma_f32 v171, v54, v154, v171
	v_cvt_pk_bf16_f32 v114, v155, v171
	ds_write_b32 v91, v114 offset:12784
	v_fma_f32 v124, v52, v155, v124
	v_fma_f32 v140, v52, v171, v140
	v_fma_f32 v124, -v54, v171, v124
	v_fma_f32 v140, v54, v155, v140
	v_cvt_pk_bf16_f32 v109, v124, v140
	ds_write_b32 v91, v109 offset:13056
	v_fma_f32 v125, v52, v124, v125
	v_fma_f32 v141, v52, v140, v141
	v_fma_f32 v125, -v54, v140, v125
	v_fma_f32 v141, v54, v124, v141
	v_cvt_pk_bf16_f32 v114, v125, v141
	ds_write_b32 v91, v114 offset:13328
	v_fma_f32 v126, v52, v125, v126
	v_fma_f32 v142, v52, v141, v142
	v_fma_f32 v126, -v54, v141, v126
	v_fma_f32 v142, v54, v125, v142
	v_cvt_pk_bf16_f32 v109, v126, v142
	ds_write_b32 v91, v109 offset:13600
	v_fma_f32 v127, v52, v126, v127
	v_fma_f32 v143, v52, v142, v143
	v_fma_f32 v127, -v54, v142, v127
	v_fma_f32 v143, v54, v126, v143
	v_cvt_pk_bf16_f32 v114, v127, v143
	ds_write_b32 v91, v114 offset:13872
	v_fma_f32 v156, v52, v127, v156
	v_fma_f32 v172, v52, v143, v172
	v_fma_f32 v156, -v54, v143, v156
	v_fma_f32 v172, v54, v127, v172
	v_cvt_pk_bf16_f32 v109, v156, v172
	ds_write_b32 v91, v109 offset:14144
	v_fma_f32 v157, v52, v156, v157
	v_fma_f32 v173, v52, v172, v173
	v_fma_f32 v157, -v54, v172, v157
	v_fma_f32 v173, v54, v156, v173
	v_cvt_pk_bf16_f32 v114, v157, v173
	ds_write_b32 v91, v114 offset:14416
	v_fma_f32 v158, v52, v157, v158
	v_fma_f32 v174, v52, v173, v174
	v_fma_f32 v158, -v54, v173, v158
	v_fma_f32 v174, v54, v157, v174
	v_cvt_pk_bf16_f32 v109, v158, v174
	ds_write_b32 v91, v109 offset:14688
	v_fma_f32 v159, v52, v158, v159
	v_fma_f32 v175, v52, v174, v175
	v_fma_f32 v159, -v54, v174, v159
	v_fma_f32 v175, v54, v158, v175
	v_cvt_pk_bf16_f32 v114, v159, v175
	ds_write_b32 v91, v114 offset:14960
	v_fma_f32 v128, v52, v159, v128
	v_fma_f32 v144, v52, v175, v144
	v_fma_f32 v128, -v54, v175, v128
	v_fma_f32 v144, v54, v159, v144
	v_cvt_pk_bf16_f32 v109, v128, v144
	ds_write_b32 v91, v109 offset:15232
	v_fma_f32 v129, v52, v128, v129
	v_fma_f32 v145, v52, v144, v145
	v_fma_f32 v129, -v54, v144, v129
	v_fma_f32 v145, v54, v128, v145
	v_cvt_pk_bf16_f32 v114, v129, v145
	ds_write_b32 v91, v114 offset:15504
	v_fma_f32 v130, v52, v129, v130
	v_fma_f32 v146, v52, v145, v146
	v_fma_f32 v130, -v54, v145, v130
	v_fma_f32 v146, v54, v129, v146
	v_cvt_pk_bf16_f32 v109, v130, v146
	ds_write_b32 v91, v109 offset:15776
	v_fma_f32 v131, v52, v130, v131
	v_fma_f32 v147, v52, v146, v147
	v_fma_f32 v131, -v54, v146, v131
	v_fma_f32 v147, v54, v130, v147
	v_cvt_pk_bf16_f32 v114, v131, v147
	ds_write_b32 v91, v114 offset:16048
	v_fma_f32 v160, v52, v131, v160
	v_fma_f32 v176, v52, v147, v176
	v_fma_f32 v160, -v54, v147, v160
	v_fma_f32 v176, v54, v131, v176
	v_cvt_pk_bf16_f32 v109, v160, v176
	ds_write_b32 v91, v109 offset:16320
	v_fma_f32 v161, v52, v160, v161
	v_fma_f32 v177, v52, v176, v177
	v_fma_f32 v161, -v54, v176, v161
	v_fma_f32 v177, v54, v160, v177
	v_cvt_pk_bf16_f32 v114, v161, v177
	ds_write_b32 v91, v114 offset:16592
	v_fma_f32 v162, v52, v161, v162
	v_fma_f32 v178, v52, v177, v178
	v_fma_f32 v162, -v54, v177, v162
	v_fma_f32 v178, v54, v161, v178
	v_cvt_pk_bf16_f32 v109, v162, v178
	ds_write_b32 v91, v109 offset:16864
	v_fma_f32 v163, v52, v162, v163
	v_fma_f32 v179, v52, v178, v179
	v_fma_f32 v163, -v54, v178, v163
	v_fma_f32 v179, v54, v162, v179
	v_cvt_pk_bf16_f32 v114, v163, v179
	ds_write_b32 v91, v114 offset:17136
	v_mov_b32_e32 v82, v163
	v_mov_b32_e32 v83, v179
	v_or_b32_e32 v82, s0, v90
	v_mov_b64_e32 v[20:21], s[42:43]
	v_mad_u64_u32 v[20:21], s[4:5], v82, s45, v[20:21]
	s_mul_i32 s0, s1, 0xa00
	v_add_u32_e32 v21, s0, v21
	v_readlane_b32 s0, v252, 1
	s_lshl_b32 s94, s0, 1
	v_lshl_add_u64 v[20:21], v[20:21], 0, s[94:95]
	v_lshl_add_u64 v[20:21], v[50:51], 1, v[20:21]
	global_load_dwordx2 v[94:95], v[20:21], off offset:1536
	v_add_co_u32_e32 v22, vcc, s28, v20
	ds_read_b128 v[24:27], v92 offset:64
	s_nop 0
	v_addc_co_u32_e32 v23, vcc, 0, v21, vcc
	global_load_dwordx2 v[88:89], v[22:23], off offset:1536
	v_add_co_u32_e32 v22, vcc, s92, v20
	v_mov_b32_e32 v83, s1
	s_nop 0
	v_addc_co_u32_e32 v23, vcc, 0, v21, vcc
	v_add_co_u32_e32 v20, vcc, s49, v20
	global_load_dwordx2 v[86:87], v[22:23], off offset:1536
	s_nop 0
	v_addc_co_u32_e32 v21, vcc, 0, v21, vcc
	global_load_dwordx2 v[84:85], v[20:21], off offset:1536
	ds_read_b128 v[20:23], v92
	s_waitcnt lgkmcnt(0)
	v_mfma_f32_16x16x32_bf16 v[20:23], v[0:3], v[20:23], 0
	v_lshlrev_b64 v[82:83], 10, v[82:83]
	v_readlane_b32 s0, v251, 20
	s_add_i32 s2, s2, s0
	v_mfma_f32_16x16x32_bf16 v[20:23], v[4:7], v[24:27], v[20:23]
	ds_read_b128 v[24:27], v92 offset:128
	s_cmpk_gt_i32 s2, 0x3fff
	v_readlane_b32 s1, v251, 21
	s_waitcnt lgkmcnt(0)
	v_mfma_f32_16x16x32_bf16 v[20:23], v[8:11], v[24:27], v[20:23]
	ds_read_b128 v[24:27], v92 offset:192
	s_waitcnt lgkmcnt(0)
	v_mfma_f32_16x16x32_bf16 v[20:23], v[12:15], v[24:27], v[20:23]
	s_waitcnt vmcnt(3)
; template <bool FINAL>
; __device__ __forceinline__ void s5_wave(const Params& P, int j, int g, int idx0, int stride, char* ldsw) {
;     ...
;     for (int mt = 0; mt < 4; ++mt) {
;       f32x4 y = {0.f, 0.f, 0.f, 0.f};
; #pragma unroll
;       for (int ks = 0; ks < 4; ++ks) {
;         bf16x8 a = *reinterpret_cast<const bf16x8*>(hbuf + (mt * 16 + fr) * 68 + ks * 16 + fq * 4);
;         y = __builtin_amdgcn_mfma_f32_16x16x32_bf16(bc[ks], a, y, 0, 0, 0);
;       }
;       const float uvf[4] = {__uint_as_float(uw[mt].x << 16), __uint_as_float(uw[mt].x & 0xffff0000u),
;                             __uint_as_float(uw[mt].y << 16), __uint_as_float(uw[mt].y & 0xffff0000u)};
;       f32x4 zo;
; #pragma unroll
;       for (int i = 0; i < 4; ++i) zo[i] = gelu_tanh(y[i] + dv4[i] * uvf[i]);
;       *reinterpret_cast<uint2*>(zs + (rowbase + mt * 16 + fr) * 512 + g * 16 + 4 * fq) = pack4(zo);
	v_lshlrev_b32_e32 v24, 16, v94
	s_nop 5
	v_fma_f32 v20, v16, v24, v20
	v_mul_f32_e32 v24, 0x3d372713, v20
	v_mul_f32_e32 v24, v20, v24
	v_fma_f32 v24, v20, v24, v20
	v_mul_f32_e32 v24, 0x3f4c422a, v24
	v_add_f32_e32 v24, v24, v24
	v_mul_f32_e32 v24, 0x3fb8aa3b, v24
	v_exp_f32_e32 v24, v24
	v_and_b32_e32 v25, 0xffff0000, v94
	v_mul_f32_e32 v20, 0.5, v20
	v_fma_f32 v21, v17, v25, v21
	v_add_f32_e32 v24, 1.0, v24
	v_rcp_f32_e32 v24, v24
	v_lshlrev_b32_e32 v26, 16, v95
	v_fma_f32 v22, v18, v26, v22
	v_and_b32_e32 v27, 0xffff0000, v95
	v_fma_f32 v24, v24, -2.0, 1.0
	v_add_f32_e32 v24, 1.0, v24
	v_mul_f32_e32 v20, v20, v24
	v_mul_f32_e32 v24, 0x3d372713, v21
	v_mul_f32_e32 v24, v21, v24
	v_fma_f32 v24, v21, v24, v21
	v_mul_f32_e32 v24, 0x3f4c422a, v24
	v_add_f32_e32 v24, v24, v24
	v_mul_f32_e32 v24, 0x3fb8aa3b, v24
	v_exp_f32_e32 v24, v24
	v_mul_f32_e32 v21, 0.5, v21
	v_fmac_f32_e32 v23, v19, v27
	v_add_f32_e32 v24, 1.0, v24
	v_rcp_f32_e32 v24, v24
	s_nop 0
	v_fma_f32 v24, v24, -2.0, 1.0
	v_add_f32_e32 v24, 1.0, v24
	v_mul_f32_e32 v21, v21, v24
	v_mul_f32_e32 v24, 0x3d372713, v22
	v_mul_f32_e32 v24, v22, v24
	v_fma_f32 v24, v22, v24, v22
	v_mul_f32_e32 v24, 0x3f4c422a, v24
	v_add_f32_e32 v24, v24, v24
	v_mul_f32_e32 v24, 0x3fb8aa3b, v24
	v_exp_f32_e32 v24, v24
	v_mul_f32_e32 v22, 0.5, v22
	v_cvt_pk_bf16_f32 v20, v20, v21
	v_add_f32_e32 v24, 1.0, v24
	v_rcp_f32_e32 v24, v24
	s_nop 0
	v_fma_f32 v24, v24, -2.0, 1.0
	v_add_f32_e32 v24, 1.0, v24
	v_mul_f32_e32 v22, v22, v24
	v_mul_f32_e32 v24, 0x3d372713, v23
	v_mul_f32_e32 v24, v23, v24
	v_fma_f32 v24, v23, v24, v23
	v_mul_f32_e32 v24, 0x3f4c422a, v24
	v_add_f32_e32 v24, v24, v24
	v_mul_f32_e32 v24, 0x3fb8aa3b, v24
	v_exp_f32_e32 v24, v24
	v_mul_f32_e32 v23, 0.5, v23
	v_add_f32_e32 v24, 1.0, v24
	v_rcp_f32_e32 v24, v24
	s_nop 0
	v_fma_f32 v24, v24, -2.0, 1.0
	v_add_f32_e32 v24, 1.0, v24
	v_mul_f32_e32 v23, v23, v24
	v_cvt_pk_bf16_f32 v21, v22, v23
	v_lshl_add_u64 v[22:23], v[70:71], 0, v[82:83]
	global_store_dwordx2 v[22:23], v[20:21], off
	ds_read_b128 v[20:23], v92 offset:4352
	ds_read_b128 v[24:27], v92 offset:4416
	s_waitcnt lgkmcnt(1)
	v_mfma_f32_16x16x32_bf16 v[20:23], v[0:3], v[20:23], 0
	s_waitcnt lgkmcnt(0)
	v_mfma_f32_16x16x32_bf16 v[20:23], v[4:7], v[24:27], v[20:23]
	ds_read_b128 v[24:27], v92 offset:4480
	s_waitcnt lgkmcnt(0)
	v_mfma_f32_16x16x32_bf16 v[20:23], v[8:11], v[24:27], v[20:23]
	ds_read_b128 v[24:27], v92 offset:4544
	s_waitcnt lgkmcnt(0)
	v_mfma_f32_16x16x32_bf16 v[20:23], v[12:15], v[24:27], v[20:23]
	s_waitcnt vmcnt(3)
	v_lshlrev_b32_e32 v24, 16, v88
	v_and_b32_e32 v25, 0xffff0000, v88
	v_lshlrev_b32_e32 v26, 16, v89
	s_nop 3
	v_fma_f32 v20, v16, v24, v20
	v_mul_f32_e32 v24, 0x3d372713, v20
	v_mul_f32_e32 v24, v20, v24
	v_fma_f32 v24, v20, v24, v20
	v_mul_f32_e32 v24, 0x3f4c422a, v24
	v_add_f32_e32 v24, v24, v24
	v_mul_f32_e32 v24, 0x3fb8aa3b, v24
	v_exp_f32_e32 v24, v24
	v_mul_f32_e32 v20, 0.5, v20
	v_fma_f32 v21, v17, v25, v21
	v_fma_f32 v22, v18, v26, v22
	v_add_f32_e32 v24, 1.0, v24
	v_rcp_f32_e32 v24, v24
	v_and_b32_e32 v27, 0xffff0000, v89
	v_fmac_f32_e32 v23, v19, v27
	v_fma_f32 v24, v24, -2.0, 1.0
	v_add_f32_e32 v24, 1.0, v24
	v_mul_f32_e32 v20, v20, v24
	v_mul_f32_e32 v24, 0x3d372713, v21
	v_mul_f32_e32 v24, v21, v24
	v_fma_f32 v24, v21, v24, v21
	v_mul_f32_e32 v24, 0x3f4c422a, v24
	v_add_f32_e32 v24, v24, v24
	v_mul_f32_e32 v24, 0x3fb8aa3b, v24
	v_exp_f32_e32 v24, v24
	v_mul_f32_e32 v21, 0.5, v21
	v_add_f32_e32 v24, 1.0, v24
	v_rcp_f32_e32 v24, v24
	s_nop 0
	v_fma_f32 v24, v24, -2.0, 1.0
	v_add_f32_e32 v24, 1.0, v24
	v_mul_f32_e32 v21, v21, v24
	v_mul_f32_e32 v24, 0x3d372713, v22
	v_mul_f32_e32 v24, v22, v24
	v_fma_f32 v24, v22, v24, v22
	v_mul_f32_e32 v24, 0x3f4c422a, v24
	v_add_f32_e32 v24, v24, v24
	v_mul_f32_e32 v24, 0x3fb8aa3b, v24
	v_exp_f32_e32 v24, v24
	v_mul_f32_e32 v22, 0.5, v22
	v_cvt_pk_bf16_f32 v20, v20, v21
	v_add_f32_e32 v24, 1.0, v24
	v_rcp_f32_e32 v24, v24
	s_nop 0
	v_fma_f32 v24, v24, -2.0, 1.0
	v_add_f32_e32 v24, 1.0, v24
	v_mul_f32_e32 v22, v22, v24
	v_mul_f32_e32 v24, 0x3d372713, v23
	v_mul_f32_e32 v24, v23, v24
	v_fma_f32 v24, v23, v24, v23
	v_mul_f32_e32 v24, 0x3f4c422a, v24
	v_add_f32_e32 v24, v24, v24
	v_mul_f32_e32 v24, 0x3fb8aa3b, v24
	v_exp_f32_e32 v24, v24
	v_mul_f32_e32 v23, 0.5, v23
	v_add_f32_e32 v24, 1.0, v24
	v_rcp_f32_e32 v24, v24
	s_nop 0
	v_fma_f32 v24, v24, -2.0, 1.0
	v_add_f32_e32 v24, 1.0, v24
	v_mul_f32_e32 v23, v23, v24
	v_cvt_pk_bf16_f32 v21, v22, v23
	v_or_b32_e32 v22, 0x4000, v82
	v_mov_b32_e32 v23, v83
	v_lshl_add_u64 v[22:23], v[70:71], 0, v[22:23]
	global_store_dwordx2 v[22:23], v[20:21], off
	ds_read_b128 v[20:23], v92 offset:8704
	ds_read_b128 v[24:27], v92 offset:8768
	s_waitcnt lgkmcnt(1)
	v_mfma_f32_16x16x32_bf16 v[20:23], v[0:3], v[20:23], 0
	s_waitcnt lgkmcnt(0)
	v_mfma_f32_16x16x32_bf16 v[20:23], v[4:7], v[24:27], v[20:23]
	ds_read_b128 v[24:27], v92 offset:8832
	s_waitcnt lgkmcnt(0)
; template <bool FINAL>
; __device__ __forceinline__ void s5_wave(const Params& P, int j, int g, int idx0, int stride, char* ldsw) {
;     ...
;     for (int mt = 0; mt < 4; ++mt) {
;       f32x4 y = {0.f, 0.f, 0.f, 0.f};
; #pragma unroll
;       for (int ks = 0; ks < 4; ++ks) {
;         bf16x8 a = *reinterpret_cast<const bf16x8*>(hbuf + (mt * 16 + fr) * 68 + ks * 16 + fq * 4);
;         y = __builtin_amdgcn_mfma_f32_16x16x32_bf16(bc[ks], a, y, 0, 0, 0);
;       }
;       const float uvf[4] = {__uint_as_float(uw[mt].x << 16), __uint_as_float(uw[mt].x & 0xffff0000u),
;                             __uint_as_float(uw[mt].y << 16), __uint_as_float(uw[mt].y & 0xffff0000u)};
;       f32x4 zo;
; #pragma unroll
;       for (int i = 0; i < 4; ++i) zo[i] = gelu_tanh(y[i] + dv4[i] * uvf[i]);
;       *reinterpret_cast<uint2*>(zs + (rowbase + mt * 16 + fr) * 512 + g * 16 + 4 * fq) = pack4(zo);
;     }
;   }
;   }
	v_mfma_f32_16x16x32_bf16 v[20:23], v[8:11], v[24:27], v[20:23]
	ds_read_b128 v[24:27], v92 offset:8896
	s_waitcnt lgkmcnt(0)
	v_mfma_f32_16x16x32_bf16 v[20:23], v[12:15], v[24:27], v[20:23]
	s_waitcnt vmcnt(3)
	v_lshlrev_b32_e32 v24, 16, v86
	v_and_b32_e32 v25, 0xffff0000, v86
	v_lshlrev_b32_e32 v26, 16, v87
	s_nop 3
	v_fma_f32 v20, v16, v24, v20
	v_mul_f32_e32 v24, 0x3d372713, v20
	v_mul_f32_e32 v24, v20, v24
	v_fma_f32 v24, v20, v24, v20
	v_mul_f32_e32 v24, 0x3f4c422a, v24
	v_add_f32_e32 v24, v24, v24
	v_mul_f32_e32 v24, 0x3fb8aa3b, v24
	v_exp_f32_e32 v24, v24
	v_mul_f32_e32 v20, 0.5, v20
	v_fma_f32 v21, v17, v25, v21
	v_fma_f32 v22, v18, v26, v22
	v_add_f32_e32 v24, 1.0, v24
	v_rcp_f32_e32 v24, v24
	v_and_b32_e32 v27, 0xffff0000, v87
	v_fmac_f32_e32 v23, v19, v27
	v_fma_f32 v24, v24, -2.0, 1.0
	v_add_f32_e32 v24, 1.0, v24
	v_mul_f32_e32 v20, v20, v24
	v_mul_f32_e32 v24, 0x3d372713, v21
	v_mul_f32_e32 v24, v21, v24
	v_fma_f32 v24, v21, v24, v21
	v_mul_f32_e32 v24, 0x3f4c422a, v24
	v_add_f32_e32 v24, v24, v24
	v_mul_f32_e32 v24, 0x3fb8aa3b, v24
	v_exp_f32_e32 v24, v24
	v_mul_f32_e32 v21, 0.5, v21
	v_add_f32_e32 v24, 1.0, v24
	v_rcp_f32_e32 v24, v24
	s_nop 0
	v_fma_f32 v24, v24, -2.0, 1.0
	v_add_f32_e32 v24, 1.0, v24
	v_mul_f32_e32 v21, v21, v24
	v_mul_f32_e32 v24, 0x3d372713, v22
	v_mul_f32_e32 v24, v22, v24
	v_fma_f32 v24, v22, v24, v22
	v_mul_f32_e32 v24, 0x3f4c422a, v24
	v_add_f32_e32 v24, v24, v24
	v_mul_f32_e32 v24, 0x3fb8aa3b, v24
	v_exp_f32_e32 v24, v24
	v_mul_f32_e32 v22, 0.5, v22
	v_cvt_pk_bf16_f32 v20, v20, v21
	v_add_f32_e32 v24, 1.0, v24
	v_rcp_f32_e32 v24, v24
	s_nop 0
	v_fma_f32 v24, v24, -2.0, 1.0
	v_add_f32_e32 v24, 1.0, v24
	v_mul_f32_e32 v22, v22, v24
	v_mul_f32_e32 v24, 0x3d372713, v23
	v_mul_f32_e32 v24, v23, v24
	v_fma_f32 v24, v23, v24, v23
	v_mul_f32_e32 v24, 0x3f4c422a, v24
	v_add_f32_e32 v24, v24, v24
	v_mul_f32_e32 v24, 0x3fb8aa3b, v24
	v_exp_f32_e32 v24, v24
	v_mul_f32_e32 v23, 0.5, v23
	v_add_f32_e32 v24, 1.0, v24
	v_rcp_f32_e32 v24, v24
	s_nop 0
	v_fma_f32 v24, v24, -2.0, 1.0
	v_add_f32_e32 v24, 1.0, v24
	v_mul_f32_e32 v23, v23, v24
	v_cvt_pk_bf16_f32 v21, v22, v23
	v_or_b32_e32 v22, 0x8000, v82
	v_mov_b32_e32 v23, v83
	v_lshl_add_u64 v[22:23], v[70:71], 0, v[22:23]
	global_store_dwordx2 v[22:23], v[20:21], off
	ds_read_b128 v[20:23], v92 offset:13056
	ds_read_b128 v[24:27], v92 offset:13120
	s_waitcnt lgkmcnt(1)
	v_mfma_f32_16x16x32_bf16 v[20:23], v[0:3], v[20:23], 0
	v_or_b32_e32 v82, 0xc000, v82
	s_waitcnt lgkmcnt(0)
	v_mfma_f32_16x16x32_bf16 v[20:23], v[4:7], v[24:27], v[20:23]
	ds_read_b128 v[24:27], v92 offset:13184
	s_waitcnt lgkmcnt(0)
	v_mfma_f32_16x16x32_bf16 v[20:23], v[8:11], v[24:27], v[20:23]
	ds_read_b128 v[24:27], v92 offset:13248
	s_waitcnt lgkmcnt(0)
	v_mfma_f32_16x16x32_bf16 v[20:23], v[12:15], v[24:27], v[20:23]
	s_waitcnt vmcnt(3)
	v_lshlrev_b32_e32 v24, 16, v84
	v_and_b32_e32 v25, 0xffff0000, v84
	v_lshlrev_b32_e32 v26, 16, v85
	s_nop 3
	v_fma_f32 v20, v16, v24, v20
	v_mul_f32_e32 v24, 0x3d372713, v20
	v_mul_f32_e32 v24, v20, v24
	v_fma_f32 v24, v20, v24, v20
	v_mul_f32_e32 v24, 0x3f4c422a, v24
	v_add_f32_e32 v24, v24, v24
	v_mul_f32_e32 v24, 0x3fb8aa3b, v24
	v_exp_f32_e32 v24, v24
	v_mul_f32_e32 v20, 0.5, v20
	v_fma_f32 v21, v17, v25, v21
	v_fma_f32 v22, v18, v26, v22
	v_add_f32_e32 v24, 1.0, v24
	v_rcp_f32_e32 v24, v24
	v_and_b32_e32 v27, 0xffff0000, v85
	v_fmac_f32_e32 v23, v19, v27
	v_fma_f32 v24, v24, -2.0, 1.0
	v_add_f32_e32 v24, 1.0, v24
	v_mul_f32_e32 v20, v20, v24
	v_mul_f32_e32 v24, 0x3d372713, v21
	v_mul_f32_e32 v24, v21, v24
	v_fma_f32 v24, v21, v24, v21
	v_mul_f32_e32 v24, 0x3f4c422a, v24
	v_add_f32_e32 v24, v24, v24
	v_mul_f32_e32 v24, 0x3fb8aa3b, v24
	v_exp_f32_e32 v24, v24
	v_mul_f32_e32 v21, 0.5, v21
	v_add_f32_e32 v24, 1.0, v24
	v_rcp_f32_e32 v24, v24
	s_nop 0
	v_fma_f32 v24, v24, -2.0, 1.0
	v_add_f32_e32 v24, 1.0, v24
	v_mul_f32_e32 v21, v21, v24
	v_mul_f32_e32 v24, 0x3d372713, v22
	v_mul_f32_e32 v24, v22, v24
	v_fma_f32 v24, v22, v24, v22
	v_mul_f32_e32 v24, 0x3f4c422a, v24
	v_add_f32_e32 v24, v24, v24
	v_mul_f32_e32 v24, 0x3fb8aa3b, v24
	v_exp_f32_e32 v24, v24
	v_mul_f32_e32 v22, 0.5, v22
	v_cvt_pk_bf16_f32 v20, v20, v21
	v_add_f32_e32 v24, 1.0, v24
	v_rcp_f32_e32 v24, v24
	s_nop 0
	v_fma_f32 v24, v24, -2.0, 1.0
	v_add_f32_e32 v24, 1.0, v24
	v_mul_f32_e32 v22, v22, v24
	v_mul_f32_e32 v24, 0x3d372713, v23
	v_mul_f32_e32 v24, v23, v24
	v_fma_f32 v24, v23, v24, v23
	v_mul_f32_e32 v24, 0x3f4c422a, v24
	v_add_f32_e32 v24, v24, v24
	v_mul_f32_e32 v24, 0x3fb8aa3b, v24
	v_exp_f32_e32 v24, v24
	v_mul_f32_e32 v23, 0.5, v23
	v_add_f32_e32 v24, 1.0, v24
	v_rcp_f32_e32 v24, v24
	s_nop 0
	v_fma_f32 v24, v24, -2.0, 1.0
	v_add_f32_e32 v24, 1.0, v24
	v_mul_f32_e32 v23, v23, v24
	v_cvt_pk_bf16_f32 v21, v22, v23
	v_lshl_add_u64 v[22:23], v[70:71], 0, v[82:83]
	global_store_dwordx2 v[22:23], v[20:21], off
	s_cbranch_scc0 .LBB0_430
